# v_c7 + attention epilogue stores widened: 16 global_store_dwordx2 per wave per half -> 8 dwordx4 via v_permlane16_swap pairs (same bytes, same addresses)
# baseline (speedup 1.0000x reference)
; #define LAS __attribute__((address_space(3)))
; __device__ __forceinline__ void attn_phase(LAS unsigned char* lds, const bf16* PROJ, bf16* MIX, const float* lq1, const float* lk1, const float* lq2, const float* lk2,
;                                            const float* norm_g, float lambda_init, int G, int wave_s) {
;     ...
;             if (mi == 1) {
; #pragma unroll
;                 for (int mt = 0; mt < 16; ++mt) *(LAS f32x4*)(XCH + ((wq * 16 + mt) * 64 + lane) * 16) = O[mt] * inv;
;             }
;             __syncthreads();
;             if (mi == 0) {
;                 float ss = 0.f;
; #pragma unroll
;                 for (int mt = 0; mt < 16; ++mt) { const f32x4 o1 = *(const LAS f32x4*)(XCH + ((wq * 16 + mt) * 64 + lane) * 16); const f32x4 o = O[mt] * inv - lam * o1; O[mt] = o;
;                     ss += (o.x * o.x + o.y * o.y) + (o.z * o.z + o.w * o.w); }
.LBB0_903:
	s_andn2_b64 vcc, exec, s[14:15]
	s_waitcnt lgkmcnt(0)
	s_barrier
	s_cbranch_vccnz .LBB0_883
	ds_read_b128 v[70:73], v68
	s_waitcnt lgkmcnt(0)
	v_pk_mul_f32 v[66:67], v[152:153], v[72:73]
	v_pk_mul_f32 v[70:71], v[150:151], v[70:71]
	v_pk_fma_f32 v[64:65], v[64:65], v[0:1], v[66:67] op_sel_hi:[1,0,1] neg_lo:[0,0,1] neg_hi:[0,0,1]
	v_pk_fma_f32 v[66:67], v[62:63], v[0:1], v[70:71] op_sel_hi:[1,0,1] neg_lo:[0,0,1] neg_hi:[0,0,1]
	ds_read_b128 v[70:73], v68 offset:1024
	v_mul_f32_e32 v62, v67, v67
	v_mul_f32_e32 v63, v65, v65
	v_fmac_f32_e32 v62, v66, v66
	v_fmac_f32_e32 v63, v64, v64
	v_add_f32_e32 v69, v62, v63
	s_waitcnt lgkmcnt(0)
	v_pk_mul_f32 v[62:63], v[152:153], v[72:73]
	v_pk_mul_f32 v[70:71], v[150:151], v[70:71]
	v_pk_fma_f32 v[60:61], v[60:61], v[0:1], v[62:63] op_sel_hi:[1,0,1] neg_lo:[0,0,1] neg_hi:[0,0,1]
	v_pk_fma_f32 v[62:63], v[58:59], v[0:1], v[70:71] op_sel_hi:[1,0,1] neg_lo:[0,0,1] neg_hi:[0,0,1]
	ds_read_b128 v[70:73], v68 offset:2048
	v_mul_f32_e32 v58, v63, v63
	v_mul_f32_e32 v59, v61, v61
	v_fmac_f32_e32 v58, v62, v62
	v_fmac_f32_e32 v59, v60, v60
	v_add_f32_e32 v58, v58, v59
	v_add_f32_e32 v69, v69, v58
	s_waitcnt lgkmcnt(0)
	v_pk_mul_f32 v[58:59], v[152:153], v[72:73]
	v_pk_mul_f32 v[70:71], v[150:151], v[70:71]
	v_pk_fma_f32 v[56:57], v[56:57], v[0:1], v[58:59] op_sel_hi:[1,0,1] neg_lo:[0,0,1] neg_hi:[0,0,1]
	v_pk_fma_f32 v[58:59], v[54:55], v[0:1], v[70:71] op_sel_hi:[1,0,1] neg_lo:[0,0,1] neg_hi:[0,0,1]
	ds_read_b128 v[70:73], v68 offset:3072
	v_mul_f32_e32 v54, v59, v59
	v_mul_f32_e32 v55, v57, v57
	v_fmac_f32_e32 v54, v58, v58
	v_fmac_f32_e32 v55, v56, v56
	v_add_f32_e32 v54, v54, v55
	v_add_f32_e32 v69, v69, v54
	s_waitcnt lgkmcnt(0)
	v_pk_mul_f32 v[54:55], v[152:153], v[72:73]
	v_pk_mul_f32 v[70:71], v[150:151], v[70:71]
	v_pk_fma_f32 v[52:53], v[52:53], v[0:1], v[54:55] op_sel_hi:[1,0,1] neg_lo:[0,0,1] neg_hi:[0,0,1]
	v_pk_fma_f32 v[54:55], v[50:51], v[0:1], v[70:71] op_sel_hi:[1,0,1] neg_lo:[0,0,1] neg_hi:[0,0,1]
	ds_read_b128 v[70:73], v68 offset:4096
	v_mul_f32_e32 v50, v55, v55
	v_mul_f32_e32 v51, v53, v53
	v_fmac_f32_e32 v50, v54, v54
	v_fmac_f32_e32 v51, v52, v52
	v_add_f32_e32 v50, v50, v51
	v_add_f32_e32 v69, v69, v50
	s_waitcnt lgkmcnt(0)
	v_pk_mul_f32 v[50:51], v[152:153], v[72:73]
	v_pk_mul_f32 v[70:71], v[150:151], v[70:71]
	v_pk_fma_f32 v[48:49], v[48:49], v[0:1], v[50:51] op_sel_hi:[1,0,1] neg_lo:[0,0,1] neg_hi:[0,0,1]
	v_pk_fma_f32 v[50:51], v[46:47], v[0:1], v[70:71] op_sel_hi:[1,0,1] neg_lo:[0,0,1] neg_hi:[0,0,1]
	ds_read_b128 v[70:73], v68 offset:5120
	v_mul_f32_e32 v46, v51, v51
	v_mul_f32_e32 v47, v49, v49
	v_fmac_f32_e32 v46, v50, v50
	v_fmac_f32_e32 v47, v48, v48
	v_add_f32_e32 v46, v46, v47
	v_add_f32_e32 v69, v69, v46
	s_waitcnt lgkmcnt(0)
	v_pk_mul_f32 v[46:47], v[152:153], v[72:73]
	v_pk_mul_f32 v[70:71], v[150:151], v[70:71]
	v_pk_fma_f32 v[44:45], v[44:45], v[0:1], v[46:47] op_sel_hi:[1,0,1] neg_lo:[0,0,1] neg_hi:[0,0,1]
	v_pk_fma_f32 v[46:47], v[42:43], v[0:1], v[70:71] op_sel_hi:[1,0,1] neg_lo:[0,0,1] neg_hi:[0,0,1]
	ds_read_b128 v[70:73], v68 offset:6144
	v_mul_f32_e32 v42, v47, v47
	v_mul_f32_e32 v43, v45, v45
	v_fmac_f32_e32 v42, v46, v46
	v_fmac_f32_e32 v43, v44, v44
	v_add_f32_e32 v42, v42, v43
	v_add_f32_e32 v69, v69, v42
	s_waitcnt lgkmcnt(0)
	v_pk_mul_f32 v[42:43], v[152:153], v[72:73]
	v_pk_mul_f32 v[70:71], v[150:151], v[70:71]
	v_pk_fma_f32 v[40:41], v[40:41], v[0:1], v[42:43] op_sel_hi:[1,0,1] neg_lo:[0,0,1] neg_hi:[0,0,1]
	v_pk_fma_f32 v[42:43], v[38:39], v[0:1], v[70:71] op_sel_hi:[1,0,1] neg_lo:[0,0,1] neg_hi:[0,0,1]
	ds_read_b128 v[70:73], v68 offset:7168
	v_mul_f32_e32 v38, v43, v43
	v_mul_f32_e32 v39, v41, v41
	v_fmac_f32_e32 v38, v42, v42
	v_fmac_f32_e32 v39, v40, v40
	v_add_f32_e32 v38, v38, v39
	v_add_f32_e32 v69, v69, v38
	s_waitcnt lgkmcnt(0)
	v_pk_mul_f32 v[38:39], v[152:153], v[72:73]
	v_pk_mul_f32 v[70:71], v[150:151], v[70:71]
	v_pk_fma_f32 v[36:37], v[36:37], v[0:1], v[38:39] op_sel_hi:[1,0,1] neg_lo:[0,0,1] neg_hi:[0,0,1]
	v_pk_fma_f32 v[38:39], v[34:35], v[0:1], v[70:71] op_sel_hi:[1,0,1] neg_lo:[0,0,1] neg_hi:[0,0,1]
	ds_read_b128 v[70:73], v68 offset:8192
	v_mul_f32_e32 v34, v39, v39
	v_mul_f32_e32 v35, v37, v37
	v_fmac_f32_e32 v34, v38, v38
	v_fmac_f32_e32 v35, v36, v36
	v_add_f32_e32 v34, v34, v35
	v_add_f32_e32 v69, v69, v34
	s_waitcnt lgkmcnt(0)
	v_pk_mul_f32 v[34:35], v[152:153], v[72:73]
	v_pk_mul_f32 v[70:71], v[150:151], v[70:71]
	v_pk_fma_f32 v[32:33], v[32:33], v[0:1], v[34:35] op_sel_hi:[1,0,1] neg_lo:[0,0,1] neg_hi:[0,0,1]
	v_pk_fma_f32 v[34:35], v[30:31], v[0:1], v[70:71] op_sel_hi:[1,0,1] neg_lo:[0,0,1] neg_hi:[0,0,1]
	ds_read_b128 v[70:73], v68 offset:9216
	v_mul_f32_e32 v30, v35, v35
	v_mul_f32_e32 v31, v33, v33
	v_fmac_f32_e32 v30, v34, v34
	v_fmac_f32_e32 v31, v32, v32
	v_add_f32_e32 v30, v30, v31
	v_add_f32_e32 v69, v69, v30
	s_waitcnt lgkmcnt(0)
	v_pk_mul_f32 v[30:31], v[152:153], v[72:73]
	v_pk_mul_f32 v[70:71], v[150:151], v[70:71]
	v_pk_fma_f32 v[28:29], v[28:29], v[0:1], v[30:31] op_sel_hi:[1,0,1] neg_lo:[0,0,1] neg_hi:[0,0,1]
	v_pk_fma_f32 v[30:31], v[26:27], v[0:1], v[70:71] op_sel_hi:[1,0,1] neg_lo:[0,0,1] neg_hi:[0,0,1]
	ds_read_b128 v[70:73], v68 offset:10240
	v_mul_f32_e32 v26, v31, v31
	v_mul_f32_e32 v27, v29, v29
	v_fmac_f32_e32 v26, v30, v30
	v_fmac_f32_e32 v27, v28, v28
	v_add_f32_e32 v26, v26, v27
	v_add_f32_e32 v69, v69, v26
	s_waitcnt lgkmcnt(0)
; __device__ __forceinline__ float xor16_sum(float v) { const auto r = __builtin_amdgcn_permlane16_swap(__float_as_uint(v), __float_as_uint(v), false, false); return __uint_as_float(r[0]) + __uint_as_float(r[1]); }
; __device__ __forceinline__ float xor32_sum(float v) { const auto r = __builtin_amdgcn_permlane32_swap(__float_as_uint(v), __float_as_uint(v), false, false); return __uint_as_float(r[0]) + __uint_as_float(r[1]); }
; #define LAS __attribute__((address_space(3)))
; __device__ __forceinline__ void attn_phase(LAS unsigned char* lds, const bf16* PROJ, bf16* MIX, const float* lq1, const float* lk1, const float* lq2, const float* lk2,
;                                            const float* norm_g, float lambda_init, int G, int wave_s) {
;     ...
;                 for (int mt = 0; mt < 16; ++mt) { const f32x4 o1 = *(const LAS f32x4*)(XCH + ((wq * 16 + mt) * 64 + lane) * 16); const f32x4 o = O[mt] * inv - lam * o1; O[mt] = o;
;                     ss += (o.x * o.x + o.y * o.y) + (o.z * o.z + o.w * o.w); }
;                 ss = xor32_sum(xor16_sum(ss));
;                 const float rs = __builtin_amdgcn_rsqf(ss * (1.0f / 256.0f) + LN_EPS) * (1.0f - lambda_init);
;                 bf16* orow = MIX + (size_t)(b * SEQ + 64 * qb + qloc) * DM + 1024 + h * 256 + 4 * q4;
; #pragma unroll
;                 for (int mt = 0; mt < 16; ++mt) { const f32x4 g = *(const f32x4*)(norm_g + 16 * mt + 4 * q4); const f32x4 o = O[mt] * rs * g;
	v_pk_mul_f32 v[26:27], v[152:153], v[72:73]
	v_pk_mul_f32 v[70:71], v[150:151], v[70:71]
	v_pk_fma_f32 v[24:25], v[24:25], v[0:1], v[26:27] op_sel_hi:[1,0,1] neg_lo:[0,0,1] neg_hi:[0,0,1]
	v_pk_fma_f32 v[26:27], v[22:23], v[0:1], v[70:71] op_sel_hi:[1,0,1] neg_lo:[0,0,1] neg_hi:[0,0,1]
	ds_read_b128 v[70:73], v68 offset:11264
	v_mul_f32_e32 v22, v27, v27
	v_mul_f32_e32 v23, v25, v25
	v_fmac_f32_e32 v22, v26, v26
	v_fmac_f32_e32 v23, v24, v24
	v_add_f32_e32 v22, v22, v23
	v_add_f32_e32 v69, v69, v22
	s_waitcnt lgkmcnt(0)
	v_pk_mul_f32 v[22:23], v[152:153], v[72:73]
	v_pk_mul_f32 v[70:71], v[150:151], v[70:71]
	v_pk_fma_f32 v[16:17], v[16:17], v[0:1], v[22:23] op_sel_hi:[1,0,1] neg_lo:[0,0,1] neg_hi:[0,0,1]
	v_pk_fma_f32 v[22:23], v[14:15], v[0:1], v[70:71] op_sel_hi:[1,0,1] neg_lo:[0,0,1] neg_hi:[0,0,1]
	ds_read_b128 v[70:73], v68 offset:12288
	v_mul_f32_e32 v14, v23, v23
	v_mul_f32_e32 v15, v17, v17
	v_fmac_f32_e32 v14, v22, v22
	v_fmac_f32_e32 v15, v16, v16
	v_add_f32_e32 v14, v14, v15
	s_waitcnt lgkmcnt(0)
	v_pk_mul_f32 v[70:71], v[150:151], v[70:71]
	v_add_f32_e32 v69, v69, v14
	v_pk_mul_f32 v[14:15], v[152:153], v[72:73]
	v_pk_fma_f32 v[18:19], v[18:19], v[0:1], v[70:71] op_sel_hi:[1,0,1] neg_lo:[0,0,1] neg_hi:[0,0,1]
	ds_read_b128 v[70:73], v68 offset:13312
	v_pk_fma_f32 v[14:15], v[20:21], v[0:1], v[14:15] op_sel_hi:[1,0,1] neg_lo:[0,0,1] neg_hi:[0,0,1]
	v_mul_f32_e32 v20, v19, v19
	v_mul_f32_e32 v21, v15, v15
	v_fmac_f32_e32 v20, v18, v18
	v_fmac_f32_e32 v21, v14, v14
	v_add_f32_e32 v20, v20, v21
	v_add_f32_e32 v69, v69, v20
	s_waitcnt lgkmcnt(0)
	v_pk_mul_f32 v[20:21], v[152:153], v[72:73]
	v_pk_mul_f32 v[70:71], v[150:151], v[70:71]
	v_pk_fma_f32 v[12:13], v[12:13], v[0:1], v[20:21] op_sel_hi:[1,0,1] neg_lo:[0,0,1] neg_hi:[0,0,1]
	v_pk_fma_f32 v[10:11], v[10:11], v[0:1], v[70:71] op_sel_hi:[1,0,1] neg_lo:[0,0,1] neg_hi:[0,0,1]
	v_mul_f32_e32 v21, v13, v13
	v_mul_f32_e32 v20, v11, v11
	v_fmac_f32_e32 v20, v10, v10
	v_fmac_f32_e32 v21, v12, v12
	v_add_f32_e32 v20, v20, v21
	v_add_f32_e32 v72, v69, v20
	ds_read_b128 v[68:71], v68 offset:14336
	s_waitcnt lgkmcnt(0)
	v_pk_mul_f32 v[20:21], v[152:153], v[70:71]
	v_pk_mul_f32 v[68:69], v[150:151], v[68:69]
	v_pk_fma_f32 v[8:9], v[8:9], v[0:1], v[20:21] op_sel_hi:[1,0,1] neg_lo:[0,0,1] neg_hi:[0,0,1]
	v_pk_fma_f32 v[6:7], v[6:7], v[0:1], v[68:69] op_sel_hi:[1,0,1] neg_lo:[0,0,1] neg_hi:[0,0,1]
	v_mul_f32_e32 v21, v9, v9
	v_mul_f32_e32 v20, v7, v7
	v_fmac_f32_e32 v20, v6, v6
	v_fmac_f32_e32 v21, v8, v8
	v_add_f32_e32 v20, v20, v21
	v_add_f32_e32 v72, v72, v20
	v_add_u32_e32 v20, s73, v170
	ds_read_b128 v[68:71], v20
	s_waitcnt lgkmcnt(0)
	v_pk_mul_f32 v[20:21], v[152:153], v[70:71]
	v_pk_mul_f32 v[68:69], v[150:151], v[68:69]
	v_pk_fma_f32 v[20:21], v[4:5], v[0:1], v[20:21] op_sel_hi:[1,0,1] neg_lo:[0,0,1] neg_hi:[0,0,1]
	v_pk_fma_f32 v[68:69], v[2:3], v[0:1], v[68:69] op_sel_hi:[1,0,1] neg_lo:[0,0,1] neg_hi:[0,0,1]
	v_mul_f32_e32 v2, v21, v21
	v_mul_f32_e32 v0, v69, v69
	v_fmac_f32_e32 v0, v68, v68
	v_fmac_f32_e32 v2, v20, v20
	v_add_f32_e32 v0, v0, v2
	v_add_f32_e32 v0, v72, v0
	v_mov_b32_e32 v2, v0
	s_nop 1
	v_permlane16_swap_b32_e32 v0, v2
	v_add_f32_e32 v0, v0, v2
	v_mov_b32_e32 v2, v0
	s_nop 1
	v_permlane32_swap_b32_e32 v0, v2
	v_add_f32_e32 v0, v0, v2
	v_or_b32_e32 v2, s85, v214
	v_ashrrev_i32_e32 v3, 31, v2
	v_lshlrev_b64 v[2:3], 12, v[2:3]
	v_lshl_add_u64 v[70:71], v[160:161], 0, v[2:3]
	global_load_dwordx4 v[82:85], v[154:155], off
	global_load_dwordx4 v[86:89], v[154:155], off offset:64
	global_load_dwordx4 v[90:93], v[154:155], off offset:128
	global_load_dwordx4 v[94:97], v[154:155], off offset:192
	global_load_dwordx4 v[98:101], v[154:155], off offset:256
	global_load_dwordx4 v[102:105], v[154:155], off offset:320
	global_load_dwordx4 v[106:109], v[154:155], off offset:384
	global_load_dwordx4 v[110:113], v[154:155], off offset:448
	global_load_dwordx4 v[114:117], v[154:155], off offset:512
	global_load_dwordx4 v[118:121], v[154:155], off offset:576
	global_load_dwordx4 v[122:125], v[154:155], off offset:640
	global_load_dwordx4 v[126:129], v[154:155], off offset:704
	global_load_dwordx4 v[130:133], v[154:155], off offset:768
	global_load_dwordx4 v[134:137], v[154:155], off offset:832
	global_load_dwordx4 v[228:231], v[154:155], off offset:896
	global_load_dwordx4 v[232:235], v[154:155], off offset:960
	v_fmamk_f32 v0, v0, 0x3b800000, v216
	v_rsq_f32_e32 v0, v0
	s_nop 0
	v_mul_f32_e32 v0, v171, v0
	v_pk_mul_f32 v[66:67], v[66:67], v[0:1] op_sel_hi:[1,0]
	v_pk_mul_f32 v[64:65], v[64:65], v[0:1] op_sel_hi:[1,0]
	v_pk_mul_f32 v[62:63], v[62:63], v[0:1] op_sel_hi:[1,0]
	v_pk_mul_f32 v[60:61], v[60:61], v[0:1] op_sel_hi:[1,0]
	v_pk_mul_f32 v[58:59], v[58:59], v[0:1] op_sel_hi:[1,0]
	v_pk_mul_f32 v[56:57], v[56:57], v[0:1] op_sel_hi:[1,0]
	v_pk_mul_f32 v[54:55], v[54:55], v[0:1] op_sel_hi:[1,0]
	v_pk_mul_f32 v[52:53], v[52:53], v[0:1] op_sel_hi:[1,0]
	v_pk_mul_f32 v[50:51], v[50:51], v[0:1] op_sel_hi:[1,0]
	v_pk_mul_f32 v[48:49], v[48:49], v[0:1] op_sel_hi:[1,0]
	v_pk_mul_f32 v[46:47], v[46:47], v[0:1] op_sel_hi:[1,0]
	v_pk_mul_f32 v[44:45], v[44:45], v[0:1] op_sel_hi:[1,0]
	v_pk_mul_f32 v[42:43], v[42:43], v[0:1] op_sel_hi:[1,0]
	v_pk_mul_f32 v[40:41], v[40:41], v[0:1] op_sel_hi:[1,0]
	v_pk_mul_f32 v[38:39], v[38:39], v[0:1] op_sel_hi:[1,0]
	v_pk_mul_f32 v[36:37], v[36:37], v[0:1] op_sel_hi:[1,0]
	v_pk_mul_f32 v[34:35], v[34:35], v[0:1] op_sel_hi:[1,0]
	v_pk_mul_f32 v[32:33], v[32:33], v[0:1] op_sel_hi:[1,0]
	v_pk_mul_f32 v[30:31], v[30:31], v[0:1] op_sel_hi:[1,0]
	v_pk_mul_f32 v[28:29], v[28:29], v[0:1] op_sel_hi:[1,0]
	v_pk_mul_f32 v[26:27], v[26:27], v[0:1] op_sel_hi:[1,0]
	v_pk_mul_f32 v[24:25], v[24:25], v[0:1] op_sel_hi:[1,0]
	v_pk_mul_f32 v[22:23], v[22:23], v[0:1] op_sel_hi:[1,0]
	v_pk_mul_f32 v[16:17], v[16:17], v[0:1] op_sel_hi:[1,0]
	v_pk_mul_f32 v[14:15], v[14:15], v[0:1] op_sel_hi:[1,0]
	v_pk_mul_f32 v[10:11], v[10:11], v[0:1] op_sel_hi:[1,0]
	v_pk_mul_f32 v[12:13], v[12:13], v[0:1] op_sel_hi:[1,0]
	v_pk_mul_f32 v[6:7], v[6:7], v[0:1] op_sel_hi:[1,0]
	v_pk_mul_f32 v[8:9], v[8:9], v[0:1] op_sel_hi:[1,0]
	s_waitcnt vmcnt(0)
; __device__ __forceinline__ unsigned pk2(float lo, float hi) { const f32x2 v = {lo, hi}; const bf16x2_n b = __builtin_convertvector(v, bf16x2_n); return __builtin_bit_cast(unsigned, b); }
; __device__ __forceinline__ void attn_phase(LAS unsigned char* lds, const bf16* PROJ, bf16* MIX, const float* lq1, const float* lk1, const float* lq2, const float* lk2,
;                                            const float* norm_g, float lambda_init, int G, int wave_s) {
;     ...
;                 for (int mt = 0; mt < 16; ++mt) { const f32x4 g = *(const f32x4*)(norm_g + 16 * mt + 4 * q4); const f32x4 o = O[mt] * rs * g;
;                     v2u wv; wv.x = pk2(o.x, o.y); wv.y = pk2(o.z, o.w); *(v2u*)(orow + 16 * mt) = wv; }
	v_pk_mul_f32 v[4:5], v[84:85], v[64:65]
	v_pk_mul_f32 v[2:3], v[82:83], v[66:67]
	v_mbcnt_lo_u32_b32 v66, -1, 0
	v_mbcnt_hi_u32_b32 v66, -1, v66
	v_bfe_u32 v66, v66, 4, 1
	v_mul_u32_u24_e32 v66, 24, v66
	v_mov_b32_e32 v67, 0
	v_lshl_add_u64 v[66:67], v[70:71], 0, v[66:67]
	s_nop 0
	v_cvt_pk_bf16_f32 v2, v2, v3
	v_cvt_pk_bf16_f32 v3, v4, v5
	v_pk_mul_f32 v[84:85], v[88:89], v[60:61]
	v_pk_mul_f32 v[82:83], v[86:87], v[62:63]
	s_nop 0
	v_cvt_pk_bf16_f32 v4, v82, v83
	v_cvt_pk_bf16_f32 v5, v84, v85
	s_nop 1
	v_permlane16_swap_b32_e32 v2, v4
	v_permlane16_swap_b32_e32 v3, v5
	global_store_dwordx4 v[66:67], v[2:5], off offset:2048
	s_nop 1
	v_pk_mul_f32 v[4:5], v[92:93], v[56:57]
	v_pk_mul_f32 v[2:3], v[90:91], v[58:59]
	s_nop 0
	v_cvt_pk_bf16_f32 v2, v2, v3
	v_cvt_pk_bf16_f32 v3, v4, v5
	v_pk_mul_f32 v[92:93], v[96:97], v[52:53]
	v_pk_mul_f32 v[90:91], v[94:95], v[54:55]
	s_nop 0
	v_cvt_pk_bf16_f32 v4, v90, v91
	v_cvt_pk_bf16_f32 v5, v92, v93
	s_nop 1
	v_permlane16_swap_b32_e32 v2, v4
	v_permlane16_swap_b32_e32 v3, v5
	global_store_dwordx4 v[66:67], v[2:5], off offset:2112
	s_nop 1
	v_pk_mul_f32 v[4:5], v[100:101], v[48:49]
	v_pk_mul_f32 v[2:3], v[98:99], v[50:51]
	s_nop 0
	v_cvt_pk_bf16_f32 v2, v2, v3
	v_cvt_pk_bf16_f32 v3, v4, v5
	v_pk_mul_f32 v[100:101], v[44:45], v[104:105]
	v_pk_mul_f32 v[98:99], v[46:47], v[102:103]
	s_nop 0
	v_cvt_pk_bf16_f32 v4, v98, v99
	v_cvt_pk_bf16_f32 v5, v100, v101
	s_nop 1
	v_permlane16_swap_b32_e32 v2, v4
	v_permlane16_swap_b32_e32 v3, v5
	global_store_dwordx4 v[66:67], v[2:5], off offset:2176
	s_nop 1
	v_pk_mul_f32 v[4:5], v[40:41], v[108:109]
	v_pk_mul_f32 v[2:3], v[42:43], v[106:107]
	s_nop 0
	v_cvt_pk_bf16_f32 v2, v2, v3
	v_cvt_pk_bf16_f32 v3, v4, v5
	v_pk_mul_f32 v[108:109], v[36:37], v[112:113]
	v_pk_mul_f32 v[106:107], v[38:39], v[110:111]
	s_nop 0
	v_cvt_pk_bf16_f32 v4, v106, v107
	v_cvt_pk_bf16_f32 v5, v108, v109
	s_nop 1
	v_permlane16_swap_b32_e32 v2, v4
	v_permlane16_swap_b32_e32 v3, v5
	global_store_dwordx4 v[66:67], v[2:5], off offset:2240
	s_nop 1
	v_pk_mul_f32 v[4:5], v[32:33], v[116:117]
	v_pk_mul_f32 v[2:3], v[34:35], v[114:115]
	s_nop 0
	v_cvt_pk_bf16_f32 v2, v2, v3
	v_cvt_pk_bf16_f32 v3, v4, v5
	v_pk_mul_f32 v[116:117], v[28:29], v[120:121]
	v_pk_mul_f32 v[114:115], v[30:31], v[118:119]
	s_nop 0
	v_cvt_pk_bf16_f32 v4, v114, v115
	v_cvt_pk_bf16_f32 v5, v116, v117
	s_nop 1
	v_permlane16_swap_b32_e32 v2, v4
	v_permlane16_swap_b32_e32 v3, v5
	global_store_dwordx4 v[66:67], v[2:5], off offset:2304
	s_nop 1
	v_pk_mul_f32 v[4:5], v[24:25], v[124:125]
	v_pk_mul_f32 v[2:3], v[26:27], v[122:123]
	s_nop 0
	v_cvt_pk_bf16_f32 v2, v2, v3
	v_cvt_pk_bf16_f32 v3, v4, v5
	v_pk_mul_f32 v[124:125], v[16:17], v[128:129]
	v_pk_mul_f32 v[122:123], v[22:23], v[126:127]
	v_pk_mul_f32 v[16:17], v[18:19], v[0:1] op_sel_hi:[1,0]
	v_cvt_pk_bf16_f32 v4, v122, v123
	v_cvt_pk_bf16_f32 v5, v124, v125
	s_nop 1
	v_permlane16_swap_b32_e32 v2, v4
	v_permlane16_swap_b32_e32 v3, v5
	global_store_dwordx4 v[66:67], v[2:5], off offset:2368
	s_nop 1
	v_pk_mul_f32 v[4:5], v[14:15], v[132:133]
	v_pk_mul_f32 v[2:3], v[16:17], v[130:131]
	s_nop 0
	v_cvt_pk_bf16_f32 v2, v2, v3
	v_cvt_pk_bf16_f32 v3, v4, v5
	v_pk_mul_f32 v[132:133], v[12:13], v[136:137]
	v_pk_mul_f32 v[130:131], v[10:11], v[134:135]
	s_nop 0
	v_cvt_pk_bf16_f32 v4, v130, v131
	v_cvt_pk_bf16_f32 v5, v132, v133
	s_nop 1
	v_permlane16_swap_b32_e32 v2, v4
	v_permlane16_swap_b32_e32 v3, v5
	global_store_dwordx4 v[66:67], v[2:5], off offset:2432
	s_nop 1
	v_pk_mul_f32 v[4:5], v[8:9], v[230:231]
	v_pk_mul_f32 v[2:3], v[6:7], v[228:229]
	v_pk_mul_f32 v[6:7], v[68:69], v[0:1] op_sel_hi:[1,0]
	v_cvt_pk_bf16_f32 v2, v2, v3
	v_cvt_pk_bf16_f32 v3, v4, v5
	v_pk_mul_f32 v[8:9], v[20:21], v[0:1] op_sel_hi:[1,0]
	v_pk_mul_f32 v[228:229], v[6:7], v[232:233]
	v_pk_mul_f32 v[230:231], v[8:9], v[234:235]
	v_cvt_pk_bf16_f32 v4, v228, v229
	v_cvt_pk_bf16_f32 v5, v230, v231
	s_nop 1
	v_permlane16_swap_b32_e32 v2, v4
	v_permlane16_swap_b32_e32 v3, v5
	global_store_dwordx4 v[66:67], v[2:5], off offset:2496
	s_nop 1
	s_branch .LBB0_883
